# prompt loop: one counted lgkmcnt wait per MFMA pair instead of one per MFMA, V read-ahead 8
# speedup vs baseline: 1.0013x; 1.0013x over previous
.LBB0_822:
	s_mov_b32 s5, 0
	v_exp_f32_e32 v124, v84
	v_exp_f32_e32 v125, v85
	v_exp_f32_e32 v126, v86
	v_add_f32_e32 v224, v124, v125
	s_waitcnt lgkmcnt(2)
	v_mfma_f32_32x32x16_bf16 v[4:19], v[164:167], v[144:147], v[4:19]
	ds_read_b64_tr_b16 v[176:177], v162 offset:29760
	ds_read_b64_tr_b16 v[178:179], v162 offset:31296
	ds_read_b64_tr_b16 v[164:165], v162 offset:32768
	ds_read_b64_tr_b16 v[166:167], v162 offset:34304
	v_exp_f32_e32 v127, v87
	v_cvt_pk_bf16_f32 v184, v124, v125
	v_mov_b32_e32 v254, v224
	v_exp_f32_e32 v128, v88
	v_mfma_f32_32x32x16_bf16 v[20:35], v[168:171], v[144:147], v[20:35]
	ds_read_b64_tr_b16 v[168:169], v162 offset:32832
	ds_read_b64_tr_b16 v[170:171], v162 offset:34368
	v_add_f32_e32 v226, v126, v127
	v_exp_f32_e32 v129, v89
	v_cvt_pk_bf16_f32 v185, v126, v127
	v_add_f32_e32 v254, v254, v226
	s_waitcnt lgkmcnt(4)
	v_mfma_f32_32x32x16_bf16 v[4:19], v[172:175], v[140:143], v[4:19]
	ds_read_b64_tr_b16 v[172:173], v162 offset:35840
	ds_read_b64_tr_b16 v[174:175], v162 offset:37376
	v_exp_f32_e32 v130, v90
	v_add_f32_e32 v233, v128, v129
	v_exp_f32_e32 v131, v91
	v_cvt_pk_bf16_f32 v186, v128, v129
	v_mfma_f32_32x32x16_bf16 v[20:35], v[176:179], v[140:143], v[20:35]
	ds_read_b64_tr_b16 v[176:177], v162 offset:35904
	ds_read_b64_tr_b16 v[178:179], v162 offset:37440
	v_add_f32_e32 v254, v254, v233
	v_exp_f32_e32 v124, v92
	v_add_f32_e32 v224, v130, v131
	v_exp_f32_e32 v125, v93
	s_waitcnt lgkmcnt(4)
	v_mfma_f32_32x32x16_bf16 v[4:19], v[164:167], v[136:139], v[4:19]
	ds_read_b128 v[180:183], v155 offset:0
	ds_read_b128 v[112:115], v155 offset:6656
	v_cvt_pk_bf16_f32 v187, v130, v131
	v_add_f32_e32 v254, v254, v224
	v_exp_f32_e32 v126, v94
	v_add_f32_e32 v226, v124, v125
	v_mfma_f32_32x32x16_bf16 v[20:35], v[168:171], v[136:139], v[20:35]
	ds_read_b128 v[116:119], v155 offset:32
	ds_read_b128 v[120:123], v155 offset:6688
	v_exp_f32_e32 v127, v95
	v_cvt_pk_bf16_f32 v188, v124, v125
	v_add_f32_e32 v254, v254, v226
	v_exp_f32_e32 v128, v96
	s_waitcnt lgkmcnt(4)
	v_mfma_f32_32x32x16_bf16 v[4:19], v[172:175], v[132:135], v[4:19]
	v_add_f32_e32 v233, v126, v127
	v_exp_f32_e32 v129, v97
	v_cvt_pk_bf16_f32 v189, v126, v127
	v_add_f32_e32 v254, v254, v233
	v_mfma_f32_32x32x16_bf16 v[20:35], v[176:179], v[132:135], v[20:35]
	v_exp_f32_e32 v130, v98
	v_add_f32_e32 v224, v128, v129
	v_exp_f32_e32 v131, v99
	v_cvt_pk_bf16_f32 v190, v128, v129
	s_waitcnt lgkmcnt(2)
	v_mfma_f32_32x32x16_bf16 v[52:67], v[180:183], v[200:203], v[234:249]
	ds_read_b128 v[180:183], v155 offset:64
	v_add_f32_e32 v254, v254, v224
	v_exp_f32_e32 v124, v36
	v_add_f32_e32 v226, v130, v131
	v_exp_f32_e32 v125, v37
	v_mfma_f32_32x32x16_bf16 v[68:83], v[112:115], v[200:203], v[234:249]
	s_barrier
	s_waitcnt vmcnt(0)
	ds_write_b128 v157, v[104:107] offset:13312
	ds_write_b64 v158, v[108:109] offset:13440
	ds_write_b128 v151, v[100:103] offset:38912
	buffer_load_dwordx2 v[108:109], v161, s[12:15], s52 offen
	s_add_i32 s3, s53, 0xfe040000
	buffer_load_dwordx4 v[104:107], v150, s[12:15], s3 offen
	buffer_load_dwordx4 v[100:103], v150, s[12:15], s53 offen
	ds_read_b128 v[112:115], v155 offset:6720
	v_cvt_pk_bf16_f32 v191, v130, v131
	v_add_f32_e32 v254, v254, v226
	v_exp_f32_e32 v126, v38
	v_add_f32_e32 v233, v124, v125
	s_waitcnt lgkmcnt(5)
	v_mfma_f32_32x32x16_bf16 v[52:67], v[116:119], v[204:207], v[52:67]
	ds_read_b128 v[116:119], v155 offset:96
	v_exp_f32_e32 v127, v39
	v_cvt_pk_bf16_f32 v192, v124, v125
	v_add_f32_e32 v254, v254, v233
	v_exp_f32_e32 v128, v40
	v_mfma_f32_32x32x16_bf16 v[68:83], v[120:123], v[204:207], v[68:83]
	ds_read_b128 v[120:123], v155 offset:6752
	v_add_f32_e32 v224, v126, v127
	v_exp_f32_e32 v129, v41
	v_cvt_pk_bf16_f32 v193, v126, v127
	v_add_f32_e32 v254, v254, v224
	s_waitcnt lgkmcnt(2)
	v_mfma_f32_32x32x16_bf16 v[52:67], v[180:183], v[208:211], v[52:67]
	s_barrier
	ds_read_b128 v[180:183], v155 offset:128
	v_exp_f32_e32 v130, v42
	v_add_f32_e32 v226, v128, v129
	v_exp_f32_e32 v131, v43
	v_cvt_pk_bf16_f32 v194, v128, v129
	v_mfma_f32_32x32x16_bf16 v[68:83], v[112:115], v[208:211], v[68:83]
	ds_read_b128 v[112:115], v155 offset:6784
	v_add_f32_e32 v254, v254, v226
	v_exp_f32_e32 v124, v44
	v_add_f32_e32 v233, v130, v131
	v_exp_f32_e32 v125, v45
	s_waitcnt lgkmcnt(2)
	v_mfma_f32_32x32x16_bf16 v[52:67], v[116:119], v[212:215], v[52:67]
	ds_read_b128 v[116:119], v155 offset:160
	v_cvt_pk_bf16_f32 v195, v130, v131
	v_add_f32_e32 v254, v254, v233
	v_exp_f32_e32 v126, v46
	v_add_f32_e32 v224, v124, v125
	v_mfma_f32_32x32x16_bf16 v[68:83], v[120:123], v[212:215], v[68:83]
	ds_read_b128 v[120:123], v155 offset:6816
	v_exp_f32_e32 v127, v47
	v_cvt_pk_bf16_f32 v196, v124, v125
	v_add_f32_e32 v254, v254, v224
	v_exp_f32_e32 v128, v48
	s_waitcnt lgkmcnt(2)
	v_mfma_f32_32x32x16_bf16 v[52:67], v[180:183], v[216:219], v[52:67]
	v_add_f32_e32 v226, v126, v127
	v_exp_f32_e32 v129, v49
	v_cvt_pk_bf16_f32 v197, v126, v127
	v_add_f32_e32 v254, v254, v226
	v_mfma_f32_32x32x16_bf16 v[68:83], v[112:115], v[216:219], v[68:83]
	v_exp_f32_e32 v130, v50
	v_add_f32_e32 v233, v128, v129
	v_exp_f32_e32 v131, v51
	v_cvt_pk_bf16_f32 v198, v128, v129
	s_waitcnt lgkmcnt(0)
	v_mfma_f32_32x32x16_bf16 v[52:67], v[116:119], v[250:253], v[52:67]
	v_add_f32_e32 v254, v254, v233
	v_add_f32_e32 v224, v130, v131
	v_cvt_pk_bf16_f32 v199, v130, v131
	v_add_f32_e32 v254, v254, v224
	v_mfma_f32_32x32x16_bf16 v[68:83], v[120:123], v[250:253], v[68:83]
	v_cmp_lt_f32_e32 vcc, 0x43800000, v254
	s_cbranch_vccnz .LpfU_s0

.LpfU_nr0:
	s_mov_b32 s5, 0
	v_exp_f32_e32 v124, v52
	v_exp_f32_e32 v125, v53
	v_exp_f32_e32 v126, v54
	v_add_f32_e32 v224, v124, v125
	s_waitcnt lgkmcnt(2)
	v_mfma_f32_32x32x16_bf16 v[4:19], v[164:167], v[184:187], v[4:19]
	ds_read_b64_tr_b16 v[176:177], v162 offset:42048
	ds_read_b64_tr_b16 v[178:179], v162 offset:43584
	ds_read_b64_tr_b16 v[164:165], v162 offset:45056
	ds_read_b64_tr_b16 v[166:167], v162 offset:46592
	v_exp_f32_e32 v127, v55
	v_cvt_pk_bf16_f32 v144, v124, v125
	v_mov_b32_e32 v254, v224
	v_exp_f32_e32 v128, v56
	v_mfma_f32_32x32x16_bf16 v[20:35], v[168:171], v[184:187], v[20:35]
	ds_read_b64_tr_b16 v[168:169], v162 offset:45120
	ds_read_b64_tr_b16 v[170:171], v162 offset:46656
	v_add_f32_e32 v226, v126, v127
	v_exp_f32_e32 v129, v57
	v_cvt_pk_bf16_f32 v145, v126, v127
	v_add_f32_e32 v254, v254, v226
	s_waitcnt lgkmcnt(4)
	v_mfma_f32_32x32x16_bf16 v[4:19], v[172:175], v[188:191], v[4:19]
	ds_read_b64_tr_b16 v[172:173], v162 offset:48128
	ds_read_b64_tr_b16 v[174:175], v162 offset:49664
	v_exp_f32_e32 v130, v58
	v_add_f32_e32 v233, v128, v129
	v_exp_f32_e32 v131, v59
	v_cvt_pk_bf16_f32 v146, v128, v129
	v_mfma_f32_32x32x16_bf16 v[20:35], v[176:179], v[188:191], v[20:35]
	ds_read_b64_tr_b16 v[176:177], v162 offset:48192
	ds_read_b64_tr_b16 v[178:179], v162 offset:49728
	v_add_f32_e32 v254, v254, v233
	v_exp_f32_e32 v124, v60
	v_add_f32_e32 v224, v130, v131
	v_exp_f32_e32 v125, v61
	s_waitcnt lgkmcnt(4)
	v_mfma_f32_32x32x16_bf16 v[4:19], v[164:167], v[192:195], v[4:19]
	ds_read_b128 v[180:183], v155 offset:13312
	ds_read_b128 v[112:115], v155 offset:19968
	v_cvt_pk_bf16_f32 v147, v130, v131
	v_add_f32_e32 v254, v254, v224
	v_exp_f32_e32 v126, v62
	v_add_f32_e32 v226, v124, v125
	v_mfma_f32_32x32x16_bf16 v[20:35], v[168:171], v[192:195], v[20:35]
	ds_read_b128 v[116:119], v155 offset:13344
	ds_read_b128 v[120:123], v155 offset:20000
	v_exp_f32_e32 v127, v63
	v_cvt_pk_bf16_f32 v140, v124, v125
	v_add_f32_e32 v254, v254, v226
	v_exp_f32_e32 v128, v64
	s_waitcnt lgkmcnt(4)
	v_mfma_f32_32x32x16_bf16 v[4:19], v[172:175], v[196:199], v[4:19]
	v_add_f32_e32 v233, v126, v127
	v_exp_f32_e32 v129, v65
	v_cvt_pk_bf16_f32 v141, v126, v127
	v_add_f32_e32 v254, v254, v233
	v_mfma_f32_32x32x16_bf16 v[20:35], v[176:179], v[196:199], v[20:35]
	v_exp_f32_e32 v130, v66
	v_add_f32_e32 v224, v128, v129
	v_exp_f32_e32 v131, v67
	v_cvt_pk_bf16_f32 v142, v128, v129
	s_waitcnt lgkmcnt(2)
	v_mfma_f32_32x32x16_bf16 v[84:99], v[180:183], v[200:203], v[234:249]
	ds_read_b128 v[180:183], v155 offset:13376
	v_add_f32_e32 v254, v254, v224
	v_exp_f32_e32 v124, v68
	v_add_f32_e32 v226, v130, v131
	v_exp_f32_e32 v125, v69
	v_mfma_f32_32x32x16_bf16 v[36:51], v[112:115], v[200:203], v[234:249]
	s_barrier
	s_waitcnt vmcnt(0)
	ds_write_b128 v157, v[104:107]
	ds_write_b64 v158, v[108:109] offset:128
	ds_write_b128 v151, v[100:103] offset:26624
	s_add_i32 s2, s51, 2
	s_cmp_lt_i32 s2, s50
	s_cbranch_scc0 .LpfU_nl
	s_add_i32 s2, s52, 0x1000
	buffer_load_dwordx2 v[108:109], v161, s[12:15], s2 offen
	s_add_i32 s3, s53, 0xfe060000
	buffer_load_dwordx4 v[104:107], v150, s[12:15], s3 offen
	s_add_i32 s4, s53, 0x20000
	buffer_load_dwordx4 v[100:103], v150, s[12:15], s4 offen
.LpfU_nl:
	ds_read_b128 v[112:115], v155 offset:20032
	v_cvt_pk_bf16_f32 v143, v130, v131
	v_add_f32_e32 v254, v254, v226
	v_exp_f32_e32 v126, v70
	v_add_f32_e32 v233, v124, v125
	s_waitcnt lgkmcnt(5)
	v_mfma_f32_32x32x16_bf16 v[84:99], v[116:119], v[204:207], v[84:99]
	ds_read_b128 v[116:119], v155 offset:13408
	v_exp_f32_e32 v127, v71
	v_cvt_pk_bf16_f32 v136, v124, v125
	v_add_f32_e32 v254, v254, v233
	v_exp_f32_e32 v128, v72
	v_mfma_f32_32x32x16_bf16 v[36:51], v[120:123], v[204:207], v[36:51]
	ds_read_b128 v[120:123], v155 offset:20064
	v_add_f32_e32 v224, v126, v127
	v_exp_f32_e32 v129, v73
	v_cvt_pk_bf16_f32 v137, v126, v127
	v_add_f32_e32 v254, v254, v224
	s_waitcnt lgkmcnt(2)
	v_mfma_f32_32x32x16_bf16 v[84:99], v[180:183], v[208:211], v[84:99]
	s_barrier
	ds_read_b128 v[180:183], v155 offset:13440
	v_exp_f32_e32 v130, v74
	v_add_f32_e32 v226, v128, v129
	v_exp_f32_e32 v131, v75
	v_cvt_pk_bf16_f32 v138, v128, v129
	v_mfma_f32_32x32x16_bf16 v[36:51], v[112:115], v[208:211], v[36:51]
	ds_read_b128 v[112:115], v155 offset:20096
	v_add_f32_e32 v254, v254, v226
	v_exp_f32_e32 v124, v76
	v_add_f32_e32 v233, v130, v131
	v_exp_f32_e32 v125, v77
	s_waitcnt lgkmcnt(2)
	v_mfma_f32_32x32x16_bf16 v[84:99], v[116:119], v[212:215], v[84:99]
	ds_read_b128 v[116:119], v155 offset:13472
	v_cvt_pk_bf16_f32 v139, v130, v131
	v_add_f32_e32 v254, v254, v233
	v_exp_f32_e32 v126, v78
	v_add_f32_e32 v224, v124, v125
	v_mfma_f32_32x32x16_bf16 v[36:51], v[120:123], v[212:215], v[36:51]
	ds_read_b128 v[120:123], v155 offset:20128
	v_exp_f32_e32 v127, v79
	v_cvt_pk_bf16_f32 v132, v124, v125
	v_add_f32_e32 v254, v254, v224
	v_exp_f32_e32 v128, v80
	s_waitcnt lgkmcnt(2)
	v_mfma_f32_32x32x16_bf16 v[84:99], v[180:183], v[216:219], v[84:99]
	v_add_f32_e32 v226, v126, v127
	v_exp_f32_e32 v129, v81
	v_cvt_pk_bf16_f32 v133, v126, v127
	v_add_f32_e32 v254, v254, v226
	v_mfma_f32_32x32x16_bf16 v[36:51], v[112:115], v[216:219], v[36:51]
	v_exp_f32_e32 v130, v82
	v_add_f32_e32 v233, v128, v129
	v_exp_f32_e32 v131, v83
	v_cvt_pk_bf16_f32 v134, v128, v129
	s_waitcnt lgkmcnt(0)
	v_mfma_f32_32x32x16_bf16 v[84:99], v[116:119], v[250:253], v[84:99]
	v_add_f32_e32 v254, v254, v233
	v_add_f32_e32 v224, v130, v131
	v_cvt_pk_bf16_f32 v135, v130, v131
	v_add_f32_e32 v254, v254, v224
	v_mfma_f32_32x32x16_bf16 v[36:51], v[120:123], v[250:253], v[36:51]
	v_cmp_lt_f32_e32 vcc, 0x43800000, v254
	s_cbranch_vccnz .LpfU_s1
